# in-proj epilogue (pn<6): 32 dwordx2 stores per wave widened to 16 dwordx4 via permlane16 swap
# speedup vs baseline: 1.0094x; 1.0035x over previous
.LBB0_1082:
	s_or_b64 s[48:49], s[56:57], s[48:49]
	v_mov_b32_e32 v144, s69
	v_mov_b32_e32 v145, s69
	v_mov_b32_e32 v146, s69
	v_mov_b32_e32 v147, s69
	v_mov_b32_e32 v124, s69
	v_mov_b32_e32 v125, s69
	v_mov_b32_e32 v126, s69
	v_mov_b32_e32 v127, s69
	s_andn2_b64 vcc, exec, s[54:55]
	v_lshlrev_b32_e32 v98, 1, v174
	v_and_b32_e32 v228, 4, v174
	v_mad_u32_u24 v98, v228, 6, v98
	s_cbranch_vccnz .LBB0_1084
	s_waitcnt lgkmcnt(0)
	v_pk_mul_f32 v[8:9], v[220:221], v[158:159]
	v_pk_mul_f32 v[10:11], v[218:219], v[156:157]
	v_pk_fma_f32 v[8:9], v[216:217], v[162:163], v[8:9] neg_lo:[0,0,1] neg_hi:[0,0,1]
	v_pk_fma_f32 v[10:11], v[214:215], v[160:161], v[10:11] neg_lo:[0,0,1] neg_hi:[0,0,1]
	v_pk_mul_f32 v[14:15], v[218:219], v[160:161]
	v_cndmask_b32_e64 v9, v217, v9, s[46:47]
	v_cndmask_b32_e64 v8, v216, v8, s[46:47]
	v_pk_fma_f32 v[14:15], v[214:215], v[156:157], v[14:15]
	v_cndmask_b32_e64 v11, v215, v11, s[46:47]
	v_cndmask_b32_e64 v10, v214, v10, s[46:47]
	v_pk_mul_f32 v[214:215], v[8:9], s[28:29] op_sel_hi:[1,0]
	v_pk_mul_f32 v[12:13], v[220:221], v[162:163]
	v_cndmask_b32_e64 v213, v9, v215, s[48:49]
	v_cndmask_b32_e64 v214, v8, v214, s[48:49]
	v_mov_b64_e32 v[8:9], s[90:91]
	v_pk_fma_f32 v[12:13], v[216:217], v[158:159], v[12:13]
	v_mad_i64_i32 v[8:9], s[24:25], v212, s85, v[8:9]
	v_cndmask_b32_e64 v13, v221, v13, s[46:47]
	v_cndmask_b32_e64 v12, v220, v12, s[46:47]
	v_cndmask_b32_e64 v15, v219, v15, s[46:47]
	v_cndmask_b32_e64 v14, v218, v14, s[46:47]
	v_pk_mul_f32 v[216:217], v[10:11], s[28:29] op_sel_hi:[1,0]
	v_lshl_add_u64 v[8:9], s[26:27], 1, v[8:9]
	s_lshl_b32 s68, s92, 1
	v_pk_mul_f32 v[218:219], v[12:13], s[28:29] op_sel_hi:[1,0]
	v_pk_mul_f32 v[220:221], v[14:15], s[28:29] op_sel_hi:[1,0]
	v_cndmask_b32_e64 v11, v11, v217, s[48:49]
	v_cndmask_b32_e64 v10, v10, v216, s[48:49]
	v_lshl_add_u64 v[8:9], v[8:9], 0, s[68:69]
	v_cndmask_b32_e64 v13, v13, v219, s[48:49]
	v_cndmask_b32_e64 v12, v12, v218, s[48:49]
	v_cndmask_b32_e64 v15, v15, v221, s[48:49]
	v_cndmask_b32_e64 v14, v14, v220, s[48:49]
	v_lshl_add_u64 v[8:9], v[8:9], 0, v[98:99]
	v_cvt_pk_bf16_f32 v180, v10, v11
	v_cvt_pk_bf16_f32 v181, v214, v213
	v_cvt_pk_bf16_f32 v182, v14, v15
	v_cvt_pk_bf16_f32 v183, v12, v13
	s_nop 1
	v_permlane16_swap_b32_e32 v180, v182
	v_permlane16_swap_b32_e32 v181, v183
	global_store_dwordx4 v[8:9], v[180:183], off
	v_pk_mul_f32 v[10:11], v[170:171], v[158:159]
	v_pk_mul_f32 v[12:13], v[168:169], v[156:157]
	v_pk_fma_f32 v[10:11], v[166:167], v[162:163], v[10:11] neg_lo:[0,0,1] neg_hi:[0,0,1]
	v_pk_fma_f32 v[12:13], v[164:165], v[160:161], v[12:13] neg_lo:[0,0,1] neg_hi:[0,0,1]
	v_pk_mul_f32 v[14:15], v[170:171], v[162:163]
	v_pk_mul_f32 v[160:161], v[168:169], v[160:161]
	s_and_b64 vcc, s[56:57], s[18:19]
	v_pk_fma_f32 v[14:15], v[166:167], v[158:159], v[14:15]
	v_pk_fma_f32 v[156:157], v[164:165], v[156:157], v[160:161]
	v_cndmask_b32_e32 v11, v167, v11, vcc
	v_cndmask_b32_e32 v10, v166, v10, vcc
	v_cndmask_b32_e32 v13, v165, v13, vcc
	v_cndmask_b32_e32 v12, v164, v12, vcc
	v_cndmask_b32_e32 v15, v171, v15, vcc
	v_cndmask_b32_e32 v14, v170, v14, vcc
	v_cndmask_b32_e32 v157, v169, v157, vcc
	v_cndmask_b32_e32 v156, v168, v156, vcc
	v_pk_mul_f32 v[12:13], v[12:13], s[28:29] op_sel_hi:[1,0]
	v_pk_mul_f32 v[10:11], v[10:11], s[28:29] op_sel_hi:[1,0]
	v_pk_mul_f32 v[156:157], v[156:157], s[28:29] op_sel_hi:[1,0]
	v_pk_mul_f32 v[14:15], v[14:15], s[28:29] op_sel_hi:[1,0]
	v_cndmask_b32_e64 v11, v167, v11, s[48:49]
	v_cndmask_b32_e64 v158, v166, v10, s[48:49]
	v_cndmask_b32_e64 v10, v165, v13, s[48:49]
	v_cndmask_b32_e64 v12, v164, v12, s[48:49]
	v_cndmask_b32_e64 v13, v171, v15, s[48:49]
	v_cndmask_b32_e64 v14, v170, v14, s[48:49]
	v_cndmask_b32_e64 v15, v169, v157, s[48:49]
	v_cndmask_b32_e64 v156, v168, v156, s[48:49]
	v_cvt_pk_bf16_f32 v180, v12, v10
	v_cvt_pk_bf16_f32 v181, v158, v11
	s_movk_i32 s68, 0x21ff
	v_cvt_pk_bf16_f32 v182, v156, v15
	v_cvt_pk_bf16_f32 v183, v14, v13
	s_nop 1
	v_permlane16_swap_b32_e32 v180, v182
	v_permlane16_swap_b32_e32 v181, v183
	global_store_dwordx4 v[8:9], v[180:183], off offset:256

.LBB0_1101:
	s_waitcnt lgkmcnt(0)
	v_pk_mul_f32 v[128:129], v[138:139], v[154:155]
	v_pk_mul_f32 v[132:133], v[138:139], v[150:151]
	v_pk_fma_f32 v[128:129], v[142:143], v[150:151], v[128:129] neg_lo:[0,0,1] neg_hi:[0,0,1]
	v_pk_fma_f32 v[132:133], v[142:143], v[154:155], v[132:133]
	v_cndmask_b32_e64 v129, v143, v129, s[46:47]
	v_cndmask_b32_e64 v128, v142, v128, s[46:47]
	v_pk_mul_f32 v[130:131], v[136:137], v[152:153]
	v_cndmask_b32_e64 v133, v139, v133, s[46:47]
	v_cndmask_b32_e64 v132, v138, v132, s[46:47]
	v_pk_mul_f32 v[138:139], v[128:129], s[28:29] op_sel_hi:[1,0]
	v_pk_fma_f32 v[130:131], v[140:141], v[148:149], v[130:131] neg_lo:[0,0,1] neg_hi:[0,0,1]
	v_pk_mul_f32 v[134:135], v[136:137], v[148:149]
	v_cndmask_b32_e64 v139, v129, v139, s[48:49]
	v_cndmask_b32_e64 v138, v128, v138, s[48:49]
	v_mov_b64_e32 v[128:129], s[90:91]
	v_pk_fma_f32 v[134:135], v[140:141], v[152:153], v[134:135]
	v_cndmask_b32_e64 v131, v141, v131, s[46:47]
	v_cndmask_b32_e64 v130, v140, v130, s[46:47]
	v_mad_i64_i32 v[128:129], s[24:25], v210, s85, v[128:129]
	v_cndmask_b32_e64 v135, v137, v135, s[46:47]
	v_cndmask_b32_e64 v134, v136, v134, s[46:47]
	v_pk_mul_f32 v[136:137], v[130:131], s[28:29] op_sel_hi:[1,0]
	v_lshl_add_u64 v[128:129], s[26:27], 1, v[128:129]
	s_lshl_b32 s68, s92, 1
	v_pk_mul_f32 v[140:141], v[134:135], s[28:29] op_sel_hi:[1,0]
	v_pk_mul_f32 v[142:143], v[132:133], s[28:29] op_sel_hi:[1,0]
	v_cndmask_b32_e64 v131, v131, v137, s[48:49]
	v_cndmask_b32_e64 v130, v130, v136, s[48:49]
	v_lshl_add_u64 v[128:129], v[128:129], 0, s[68:69]
	v_cndmask_b32_e64 v133, v133, v143, s[48:49]
	v_cndmask_b32_e64 v132, v132, v142, s[48:49]
	v_cndmask_b32_e64 v135, v135, v141, s[48:49]
	v_cndmask_b32_e64 v134, v134, v140, s[48:49]
	v_lshl_add_u64 v[128:129], v[128:129], 0, v[98:99]
	v_cvt_pk_bf16_f32 v180, v130, v131
	v_cvt_pk_bf16_f32 v181, v138, v139
	v_cvt_pk_bf16_f32 v182, v134, v135
	v_cvt_pk_bf16_f32 v183, v132, v133
	s_nop 1
	v_permlane16_swap_b32_e32 v180, v182
	v_permlane16_swap_b32_e32 v181, v183
	global_store_dwordx4 v[128:129], v[180:183], off
	v_pk_mul_f32 v[130:131], v[14:15], v[154:155]
	v_pk_mul_f32 v[132:133], v[12:13], v[152:153]
	v_pk_fma_f32 v[130:131], v[10:11], v[150:151], v[130:131] neg_lo:[0,0,1] neg_hi:[0,0,1]
	v_pk_fma_f32 v[132:133], v[8:9], v[148:149], v[132:133] neg_lo:[0,0,1] neg_hi:[0,0,1]
	v_pk_mul_f32 v[134:135], v[14:15], v[150:151]
	v_pk_mul_f32 v[136:137], v[12:13], v[148:149]
	s_and_b64 vcc, s[56:57], s[18:19]
	v_pk_fma_f32 v[136:137], v[8:9], v[152:153], v[136:137]
	v_pk_fma_f32 v[134:135], v[10:11], v[154:155], v[134:135]
	v_cndmask_b32_e32 v131, v11, v131, vcc
	v_cndmask_b32_e32 v130, v10, v130, vcc
	v_cndmask_b32_e32 v133, v9, v133, vcc
	v_cndmask_b32_e32 v132, v8, v132, vcc
	v_cndmask_b32_e32 v135, v15, v135, vcc
	v_cndmask_b32_e32 v134, v14, v134, vcc
	v_cndmask_b32_e32 v137, v13, v137, vcc
	v_cndmask_b32_e32 v136, v12, v136, vcc
	v_pk_mul_f32 v[132:133], v[132:133], s[28:29] op_sel_hi:[1,0]
	v_pk_mul_f32 v[130:131], v[130:131], s[28:29] op_sel_hi:[1,0]
	v_pk_mul_f32 v[136:137], v[136:137], s[28:29] op_sel_hi:[1,0]
	v_pk_mul_f32 v[134:135], v[134:135], s[28:29] op_sel_hi:[1,0]
	v_cndmask_b32_e64 v11, v11, v131, s[48:49]
	v_cndmask_b32_e64 v10, v10, v130, s[48:49]
	v_cndmask_b32_e64 v9, v9, v133, s[48:49]
	v_cndmask_b32_e64 v8, v8, v132, s[48:49]
	v_cndmask_b32_e64 v15, v15, v135, s[48:49]
	v_cndmask_b32_e64 v14, v14, v134, s[48:49]
	v_cndmask_b32_e64 v13, v13, v137, s[48:49]
	v_cndmask_b32_e64 v12, v12, v136, s[48:49]
	v_cvt_pk_bf16_f32 v180, v8, v9
	v_cvt_pk_bf16_f32 v181, v10, v11
	s_movk_i32 s68, 0x21ff
	v_cvt_pk_bf16_f32 v182, v12, v13
	v_cvt_pk_bf16_f32 v183, v14, v15
	s_nop 1
	v_permlane16_swap_b32_e32 v180, v182
	v_permlane16_swap_b32_e32 v181, v183
	global_store_dwordx4 v[128:129], v[180:183], off offset:256
	s_and_b64 vcc, exec, s[50:51]
	s_cbranch_vccz .LBB0_1099

.LBB0_1117:
	s_andn2_b64 vcc, exec, s[60:61]
	s_cbranch_vccnz .LBB0_1119
	s_waitcnt vmcnt(0) lgkmcnt(0)
	v_pk_mul_f32 v[116:117], v[134:135], v[146:147]
	v_pk_mul_f32 v[120:121], v[134:135], v[14:15]
	v_pk_fma_f32 v[116:117], v[130:131], v[14:15], v[116:117] neg_lo:[0,0,1] neg_hi:[0,0,1]
	v_pk_mul_f32 v[118:119], v[132:133], v[144:145]
	v_cndmask_b32_e64 v117, v131, v117, s[46:47]
	v_cndmask_b32_e64 v116, v130, v116, s[46:47]
	v_pk_fma_f32 v[120:121], v[130:131], v[146:147], v[120:121]
	v_pk_mul_f32 v[130:131], v[116:117], s[28:29] op_sel_hi:[1,0]
	v_pk_fma_f32 v[118:119], v[128:129], v[12:13], v[118:119] neg_lo:[0,0,1] neg_hi:[0,0,1]
	v_pk_mul_f32 v[122:123], v[132:133], v[12:13]
	v_cndmask_b32_e64 v131, v117, v131, s[48:49]
	v_cndmask_b32_e64 v130, v116, v130, s[48:49]
	v_mov_b64_e32 v[116:117], s[90:91]
	v_pk_fma_f32 v[122:123], v[128:129], v[144:145], v[122:123]
	v_cndmask_b32_e64 v119, v129, v119, s[46:47]
	v_cndmask_b32_e64 v118, v128, v118, s[46:47]
	v_mad_i64_i32 v[116:117], s[24:25], v208, s85, v[116:117]
	v_cndmask_b32_e64 v121, v135, v121, s[46:47]
	v_cndmask_b32_e64 v120, v134, v120, s[46:47]
	v_cndmask_b32_e64 v123, v133, v123, s[46:47]
	v_cndmask_b32_e64 v122, v132, v122, s[46:47]
	v_pk_mul_f32 v[128:129], v[118:119], s[28:29] op_sel_hi:[1,0]
	v_lshl_add_u64 v[116:117], s[26:27], 1, v[116:117]
	s_lshl_b32 s68, s92, 1
	v_pk_mul_f32 v[132:133], v[122:123], s[28:29] op_sel_hi:[1,0]
	v_pk_mul_f32 v[134:135], v[120:121], s[28:29] op_sel_hi:[1,0]
	v_cndmask_b32_e64 v119, v119, v129, s[48:49]
	v_cndmask_b32_e64 v118, v118, v128, s[48:49]
	v_lshl_add_u64 v[116:117], v[116:117], 0, s[68:69]
	v_cndmask_b32_e64 v121, v121, v135, s[48:49]
	v_cndmask_b32_e64 v120, v120, v134, s[48:49]
	v_cndmask_b32_e64 v123, v123, v133, s[48:49]
	v_cndmask_b32_e64 v122, v122, v132, s[48:49]
	v_lshl_add_u64 v[116:117], v[116:117], 0, v[98:99]
	v_cvt_pk_bf16_f32 v180, v118, v119
	v_cvt_pk_bf16_f32 v181, v130, v131
	v_cvt_pk_bf16_f32 v182, v122, v123
	v_cvt_pk_bf16_f32 v183, v120, v121
	s_nop 1
	v_permlane16_swap_b32_e32 v180, v182
	v_permlane16_swap_b32_e32 v181, v183
	global_store_dwordx4 v[116:117], v[180:183], off
	v_pk_mul_f32 v[118:119], v[110:111], v[146:147]
	v_pk_mul_f32 v[120:121], v[108:109], v[144:145]
	v_pk_fma_f32 v[118:119], v[114:115], v[14:15], v[118:119] neg_lo:[0,0,1] neg_hi:[0,0,1]
	v_pk_fma_f32 v[120:121], v[112:113], v[12:13], v[120:121] neg_lo:[0,0,1] neg_hi:[0,0,1]
	v_pk_mul_f32 v[14:15], v[110:111], v[14:15]
	v_pk_mul_f32 v[12:13], v[108:109], v[12:13]
	s_and_b64 vcc, s[56:57], s[18:19]
	v_pk_fma_f32 v[12:13], v[112:113], v[144:145], v[12:13]
	v_pk_fma_f32 v[14:15], v[114:115], v[146:147], v[14:15]
	v_cndmask_b32_e32 v119, v115, v119, vcc
	v_cndmask_b32_e32 v118, v114, v118, vcc
	v_cndmask_b32_e32 v121, v113, v121, vcc
	v_cndmask_b32_e32 v120, v112, v120, vcc
	v_cndmask_b32_e32 v15, v111, v15, vcc
	v_cndmask_b32_e32 v14, v110, v14, vcc
	v_cndmask_b32_e32 v13, v109, v13, vcc
	v_cndmask_b32_e32 v12, v108, v12, vcc
	v_pk_mul_f32 v[120:121], v[120:121], s[28:29] op_sel_hi:[1,0]
	v_pk_mul_f32 v[118:119], v[118:119], s[28:29] op_sel_hi:[1,0]
	v_pk_mul_f32 v[12:13], v[12:13], s[28:29] op_sel_hi:[1,0]
	v_pk_mul_f32 v[14:15], v[14:15], s[28:29] op_sel_hi:[1,0]
	v_cndmask_b32_e64 v115, v115, v119, s[48:49]
	v_cndmask_b32_e64 v114, v114, v118, s[48:49]
	v_cndmask_b32_e64 v113, v113, v121, s[48:49]
	v_cndmask_b32_e64 v112, v112, v120, s[48:49]
	v_cndmask_b32_e64 v15, v111, v15, s[48:49]
	v_cndmask_b32_e64 v14, v110, v14, s[48:49]
	v_cndmask_b32_e64 v109, v109, v13, s[48:49]
	v_cndmask_b32_e64 v108, v108, v12, s[48:49]
	v_cvt_pk_bf16_f32 v180, v112, v113
	v_cvt_pk_bf16_f32 v181, v114, v115
	s_movk_i32 s68, 0x21ff
	v_cvt_pk_bf16_f32 v182, v108, v109
	v_cvt_pk_bf16_f32 v183, v14, v15
	s_nop 1
	v_permlane16_swap_b32_e32 v180, v182
	v_permlane16_swap_b32_e32 v181, v183
	global_store_dwordx4 v[116:117], v[180:183], off offset:256

.LBB0_1136:
	s_waitcnt lgkmcnt(0)
	v_pk_mul_f32 v[92:93], v[110:111], v[126:127]
	v_pk_mul_f32 v[100:101], v[110:111], v[10:11]
	v_pk_fma_f32 v[92:93], v[106:107], v[10:11], v[92:93] neg_lo:[0,0,1] neg_hi:[0,0,1]
	v_pk_mul_f32 v[94:95], v[108:109], v[124:125]
	v_cndmask_b32_e64 v93, v107, v93, s[46:47]
	v_cndmask_b32_e64 v92, v106, v92, s[46:47]
	v_pk_fma_f32 v[100:101], v[106:107], v[126:127], v[100:101]
	v_pk_mul_f32 v[106:107], v[92:93], s[28:29] op_sel_hi:[1,0]
	v_pk_fma_f32 v[94:95], v[104:105], v[8:9], v[94:95] neg_lo:[0,0,1] neg_hi:[0,0,1]
	v_pk_mul_f32 v[102:103], v[108:109], v[8:9]
	v_cndmask_b32_e64 v107, v93, v107, s[48:49]
	v_cndmask_b32_e64 v106, v92, v106, s[48:49]
	v_mov_b64_e32 v[92:93], s[90:91]
	v_pk_fma_f32 v[102:103], v[104:105], v[124:125], v[102:103]
	v_cndmask_b32_e64 v95, v105, v95, s[46:47]
	v_cndmask_b32_e64 v94, v104, v94, s[46:47]
	v_mad_i64_i32 v[92:93], s[24:25], v206, s85, v[92:93]
	v_cndmask_b32_e64 v101, v111, v101, s[46:47]
	v_cndmask_b32_e64 v100, v110, v100, s[46:47]
	v_cndmask_b32_e64 v103, v109, v103, s[46:47]
	v_cndmask_b32_e64 v102, v108, v102, s[46:47]
	v_pk_mul_f32 v[104:105], v[94:95], s[28:29] op_sel_hi:[1,0]
	v_lshl_add_u64 v[92:93], s[26:27], 1, v[92:93]
	s_lshl_b32 s68, s92, 1
	v_pk_mul_f32 v[108:109], v[102:103], s[28:29] op_sel_hi:[1,0]
	v_pk_mul_f32 v[110:111], v[100:101], s[28:29] op_sel_hi:[1,0]
	v_cndmask_b32_e64 v95, v95, v105, s[48:49]
	v_cndmask_b32_e64 v94, v94, v104, s[48:49]
	v_lshl_add_u64 v[92:93], v[92:93], 0, s[68:69]
	v_cndmask_b32_e64 v101, v101, v111, s[48:49]
	v_cndmask_b32_e64 v100, v100, v110, s[48:49]
	v_cndmask_b32_e64 v103, v103, v109, s[48:49]
	v_cndmask_b32_e64 v102, v102, v108, s[48:49]
	v_lshl_add_u64 v[92:93], v[92:93], 0, v[98:99]
	v_cvt_pk_bf16_f32 v180, v94, v95
	v_cvt_pk_bf16_f32 v181, v106, v107
	v_cvt_pk_bf16_f32 v182, v102, v103
	v_cvt_pk_bf16_f32 v183, v100, v101
	s_nop 1
	v_permlane16_swap_b32_e32 v180, v182
	v_permlane16_swap_b32_e32 v181, v183
	global_store_dwordx4 v[92:93], v[180:183], off
	v_pk_mul_f32 v[94:95], v[90:91], v[126:127]
	v_pk_mul_f32 v[100:101], v[88:89], v[124:125]
	v_pk_fma_f32 v[94:95], v[14:15], v[10:11], v[94:95] neg_lo:[0,0,1] neg_hi:[0,0,1]
	v_pk_fma_f32 v[100:101], v[12:13], v[8:9], v[100:101] neg_lo:[0,0,1] neg_hi:[0,0,1]
	v_pk_mul_f32 v[10:11], v[90:91], v[10:11]
	v_pk_mul_f32 v[8:9], v[88:89], v[8:9]
	s_and_b64 vcc, s[56:57], s[18:19]
	v_pk_fma_f32 v[8:9], v[12:13], v[124:125], v[8:9]
	v_pk_fma_f32 v[10:11], v[14:15], v[126:127], v[10:11]
	v_cndmask_b32_e32 v95, v15, v95, vcc
	v_cndmask_b32_e32 v94, v14, v94, vcc
	v_cndmask_b32_e32 v101, v13, v101, vcc
	v_cndmask_b32_e32 v100, v12, v100, vcc
	v_cndmask_b32_e32 v11, v91, v11, vcc
	v_cndmask_b32_e32 v10, v90, v10, vcc
	v_cndmask_b32_e32 v9, v89, v9, vcc
	v_cndmask_b32_e32 v8, v88, v8, vcc
	v_pk_mul_f32 v[100:101], v[100:101], s[28:29] op_sel_hi:[1,0]
	v_pk_mul_f32 v[94:95], v[94:95], s[28:29] op_sel_hi:[1,0]
	v_pk_mul_f32 v[8:9], v[8:9], s[28:29] op_sel_hi:[1,0]
	v_pk_mul_f32 v[10:11], v[10:11], s[28:29] op_sel_hi:[1,0]
	v_cndmask_b32_e64 v15, v15, v95, s[48:49]
	v_cndmask_b32_e64 v14, v14, v94, s[48:49]
	v_cndmask_b32_e64 v13, v13, v101, s[48:49]
	v_cndmask_b32_e64 v12, v12, v100, s[48:49]
	v_cndmask_b32_e64 v11, v91, v11, s[48:49]
	v_cndmask_b32_e64 v10, v90, v10, s[48:49]
	v_cndmask_b32_e64 v89, v89, v9, s[48:49]
	v_cndmask_b32_e64 v88, v88, v8, s[48:49]
	v_cvt_pk_bf16_f32 v180, v12, v13
	v_cvt_pk_bf16_f32 v181, v14, v15
	s_movk_i32 s68, 0x21ff
	v_cvt_pk_bf16_f32 v182, v88, v89
	v_cvt_pk_bf16_f32 v183, v10, v11
	s_nop 1
	v_permlane16_swap_b32_e32 v180, v182
	v_permlane16_swap_b32_e32 v181, v183
	global_store_dwordx4 v[92:93], v[180:183], off offset:256
	s_and_b64 vcc, exec, s[50:51]
	s_cbranch_vccz .LBB0_1134

.LBB0_1152:
	s_andn2_b64 vcc, exec, s[60:61]
	s_cbranch_vccnz .LBB0_1154
	s_waitcnt vmcnt(0) lgkmcnt(0)
	v_pk_mul_f32 v[80:81], v[106:107], v[90:91]
	v_pk_mul_f32 v[82:83], v[104:105], v[88:89]
	v_pk_fma_f32 v[80:81], v[102:103], v[94:95], v[80:81] neg_lo:[0,0,1] neg_hi:[0,0,1]
	v_pk_fma_f32 v[82:83], v[100:101], v[92:93], v[82:83] neg_lo:[0,0,1] neg_hi:[0,0,1]
	v_pk_mul_f32 v[86:87], v[104:105], v[92:93]
	v_cndmask_b32_e64 v81, v103, v81, s[46:47]
	v_cndmask_b32_e64 v80, v102, v80, s[46:47]
	v_pk_fma_f32 v[86:87], v[100:101], v[88:89], v[86:87]
	v_cndmask_b32_e64 v83, v101, v83, s[46:47]
	v_cndmask_b32_e64 v82, v100, v82, s[46:47]
	v_pk_mul_f32 v[100:101], v[80:81], s[28:29] op_sel_hi:[1,0]
	v_pk_mul_f32 v[84:85], v[106:107], v[94:95]
	v_cndmask_b32_e64 v101, v81, v101, s[48:49]
	v_cndmask_b32_e64 v100, v80, v100, s[48:49]
	v_mov_b64_e32 v[80:81], s[90:91]
	v_pk_fma_f32 v[84:85], v[102:103], v[90:91], v[84:85]
	v_mad_i64_i32 v[80:81], s[24:25], v204, s85, v[80:81]
	v_cndmask_b32_e64 v85, v107, v85, s[46:47]
	v_cndmask_b32_e64 v84, v106, v84, s[46:47]
	v_cndmask_b32_e64 v87, v105, v87, s[46:47]
	v_cndmask_b32_e64 v86, v104, v86, s[46:47]
	v_pk_mul_f32 v[102:103], v[82:83], s[28:29] op_sel_hi:[1,0]
	v_lshl_add_u64 v[80:81], s[26:27], 1, v[80:81]
	s_lshl_b32 s68, s92, 1
	v_pk_mul_f32 v[104:105], v[84:85], s[28:29] op_sel_hi:[1,0]
	v_pk_mul_f32 v[106:107], v[86:87], s[28:29] op_sel_hi:[1,0]
	v_cndmask_b32_e64 v83, v83, v103, s[48:49]
	v_cndmask_b32_e64 v82, v82, v102, s[48:49]
	v_lshl_add_u64 v[80:81], v[80:81], 0, s[68:69]
	v_cndmask_b32_e64 v85, v85, v105, s[48:49]
	v_cndmask_b32_e64 v84, v84, v104, s[48:49]
	v_cndmask_b32_e64 v87, v87, v107, s[48:49]
	v_cndmask_b32_e64 v86, v86, v106, s[48:49]
	v_lshl_add_u64 v[80:81], v[80:81], 0, v[98:99]
	v_cvt_pk_bf16_f32 v180, v82, v83
	v_cvt_pk_bf16_f32 v181, v100, v101
	v_cvt_pk_bf16_f32 v182, v86, v87
	v_cvt_pk_bf16_f32 v183, v84, v85
	s_nop 1
	v_permlane16_swap_b32_e32 v180, v182
	v_permlane16_swap_b32_e32 v181, v183
	global_store_dwordx4 v[80:81], v[180:183], off
	v_pk_mul_f32 v[82:83], v[74:75], v[90:91]
	v_pk_mul_f32 v[84:85], v[72:73], v[88:89]
	v_pk_fma_f32 v[82:83], v[78:79], v[94:95], v[82:83] neg_lo:[0,0,1] neg_hi:[0,0,1]
	v_pk_fma_f32 v[84:85], v[76:77], v[92:93], v[84:85] neg_lo:[0,0,1] neg_hi:[0,0,1]
	v_pk_mul_f32 v[86:87], v[74:75], v[94:95]
	v_pk_mul_f32 v[92:93], v[72:73], v[92:93]
	s_and_b64 vcc, s[56:57], s[18:19]
	v_pk_fma_f32 v[86:87], v[78:79], v[90:91], v[86:87]
	v_pk_fma_f32 v[88:89], v[76:77], v[88:89], v[92:93]
	v_cndmask_b32_e32 v83, v79, v83, vcc
	v_cndmask_b32_e32 v82, v78, v82, vcc
	v_cndmask_b32_e32 v85, v77, v85, vcc
	v_cndmask_b32_e32 v84, v76, v84, vcc
	v_cndmask_b32_e32 v87, v75, v87, vcc
	v_cndmask_b32_e32 v86, v74, v86, vcc
	v_cndmask_b32_e32 v89, v73, v89, vcc
	v_cndmask_b32_e32 v88, v72, v88, vcc
	v_pk_mul_f32 v[84:85], v[84:85], s[28:29] op_sel_hi:[1,0]
	v_pk_mul_f32 v[82:83], v[82:83], s[28:29] op_sel_hi:[1,0]
	v_pk_mul_f32 v[88:89], v[88:89], s[28:29] op_sel_hi:[1,0]
	v_pk_mul_f32 v[86:87], v[86:87], s[28:29] op_sel_hi:[1,0]
	v_cndmask_b32_e64 v79, v79, v83, s[48:49]
	v_cndmask_b32_e64 v78, v78, v82, s[48:49]
	v_cndmask_b32_e64 v77, v77, v85, s[48:49]
	v_cndmask_b32_e64 v76, v76, v84, s[48:49]
	v_cndmask_b32_e64 v75, v75, v87, s[48:49]
	v_cndmask_b32_e64 v74, v74, v86, s[48:49]
	v_cndmask_b32_e64 v82, v73, v89, s[48:49]
	v_cndmask_b32_e64 v83, v72, v88, s[48:49]
	v_cvt_pk_bf16_f32 v180, v76, v77
	v_cvt_pk_bf16_f32 v181, v78, v79
	s_movk_i32 s68, 0x21ff
	v_cvt_pk_bf16_f32 v182, v83, v82
	v_cvt_pk_bf16_f32 v183, v74, v75
	s_nop 1
	v_permlane16_swap_b32_e32 v180, v182
	v_permlane16_swap_b32_e32 v181, v183
	global_store_dwordx4 v[80:81], v[180:183], off offset:256

.LBB0_1171:
	s_waitcnt vmcnt(0) lgkmcnt(0)
	v_pk_mul_f32 v[64:65], v[78:79], v[10:11]
	v_pk_mul_f32 v[68:69], v[78:79], v[14:15]
	v_pk_fma_f32 v[64:65], v[74:75], v[14:15], v[64:65] neg_lo:[0,0,1] neg_hi:[0,0,1]
	v_pk_mul_f32 v[66:67], v[76:77], v[8:9]
	v_cndmask_b32_e64 v65, v75, v65, s[46:47]
	v_cndmask_b32_e64 v64, v74, v64, s[46:47]
	v_pk_fma_f32 v[68:69], v[74:75], v[10:11], v[68:69]
	v_pk_mul_f32 v[74:75], v[64:65], s[28:29] op_sel_hi:[1,0]
	v_pk_fma_f32 v[66:67], v[72:73], v[12:13], v[66:67] neg_lo:[0,0,1] neg_hi:[0,0,1]
	v_pk_mul_f32 v[70:71], v[76:77], v[12:13]
	v_cndmask_b32_e64 v75, v65, v75, s[48:49]
	v_cndmask_b32_e64 v74, v64, v74, s[48:49]
	v_mov_b64_e32 v[64:65], s[90:91]
	v_pk_fma_f32 v[70:71], v[72:73], v[8:9], v[70:71]
	v_cndmask_b32_e64 v67, v73, v67, s[46:47]
	v_cndmask_b32_e64 v66, v72, v66, s[46:47]
	v_mad_i64_i32 v[64:65], s[24:25], v202, s85, v[64:65]
	v_cndmask_b32_e64 v69, v79, v69, s[46:47]
	v_cndmask_b32_e64 v68, v78, v68, s[46:47]
	v_cndmask_b32_e64 v71, v77, v71, s[46:47]
	v_cndmask_b32_e64 v70, v76, v70, s[46:47]
	v_pk_mul_f32 v[72:73], v[66:67], s[28:29] op_sel_hi:[1,0]
	v_lshl_add_u64 v[64:65], s[26:27], 1, v[64:65]
	s_lshl_b32 s68, s92, 1
	v_pk_mul_f32 v[76:77], v[70:71], s[28:29] op_sel_hi:[1,0]
	v_pk_mul_f32 v[78:79], v[68:69], s[28:29] op_sel_hi:[1,0]
	v_cndmask_b32_e64 v67, v67, v73, s[48:49]
	v_cndmask_b32_e64 v66, v66, v72, s[48:49]
	v_lshl_add_u64 v[64:65], v[64:65], 0, s[68:69]
	v_cndmask_b32_e64 v69, v69, v79, s[48:49]
	v_cndmask_b32_e64 v68, v68, v78, s[48:49]
	v_cndmask_b32_e64 v71, v71, v77, s[48:49]
	v_cndmask_b32_e64 v70, v70, v76, s[48:49]
	v_lshl_add_u64 v[64:65], v[64:65], 0, v[98:99]
	v_cvt_pk_bf16_f32 v180, v66, v67
	v_cvt_pk_bf16_f32 v181, v74, v75
	v_cvt_pk_bf16_f32 v182, v70, v71
	v_cvt_pk_bf16_f32 v183, v68, v69
	s_nop 1
	v_permlane16_swap_b32_e32 v180, v182
	v_permlane16_swap_b32_e32 v181, v183
	global_store_dwordx4 v[64:65], v[180:183], off
	v_pk_mul_f32 v[66:67], v[58:59], v[10:11]
	v_pk_mul_f32 v[68:69], v[56:57], v[8:9]
	v_pk_fma_f32 v[66:67], v[62:63], v[14:15], v[66:67] neg_lo:[0,0,1] neg_hi:[0,0,1]
	v_pk_fma_f32 v[68:69], v[60:61], v[12:13], v[68:69] neg_lo:[0,0,1] neg_hi:[0,0,1]
	v_pk_mul_f32 v[14:15], v[58:59], v[14:15]
	v_pk_mul_f32 v[12:13], v[56:57], v[12:13]
	s_and_b64 vcc, s[56:57], s[18:19]
	v_pk_fma_f32 v[8:9], v[60:61], v[8:9], v[12:13]
	v_pk_fma_f32 v[10:11], v[62:63], v[10:11], v[14:15]
	v_cndmask_b32_e32 v13, v63, v67, vcc
	v_cndmask_b32_e32 v12, v62, v66, vcc
	v_cndmask_b32_e32 v15, v61, v69, vcc
	v_cndmask_b32_e32 v14, v60, v68, vcc
	v_cndmask_b32_e32 v11, v59, v11, vcc
	v_cndmask_b32_e32 v10, v58, v10, vcc
	v_cndmask_b32_e32 v9, v57, v9, vcc
	v_cndmask_b32_e32 v8, v56, v8, vcc
	v_pk_mul_f32 v[14:15], v[14:15], s[28:29] op_sel_hi:[1,0]
	v_pk_mul_f32 v[12:13], v[12:13], s[28:29] op_sel_hi:[1,0]
	v_pk_mul_f32 v[8:9], v[8:9], s[28:29] op_sel_hi:[1,0]
	v_pk_mul_f32 v[10:11], v[10:11], s[28:29] op_sel_hi:[1,0]
	v_cndmask_b32_e64 v13, v63, v13, s[48:49]
	v_cndmask_b32_e64 v12, v62, v12, s[48:49]
	v_cndmask_b32_e64 v15, v61, v15, s[48:49]
	v_cndmask_b32_e64 v14, v60, v14, s[48:49]
	v_cndmask_b32_e64 v11, v59, v11, s[48:49]
	v_cndmask_b32_e64 v10, v58, v10, s[48:49]
	v_cndmask_b32_e64 v57, v57, v9, s[48:49]
	v_cndmask_b32_e64 v56, v56, v8, s[48:49]
	v_cvt_pk_bf16_f32 v180, v14, v15
	v_cvt_pk_bf16_f32 v181, v12, v13
	s_movk_i32 s68, 0x21ff
	v_cvt_pk_bf16_f32 v182, v56, v57
	v_cvt_pk_bf16_f32 v183, v10, v11
	s_nop 1
	v_permlane16_swap_b32_e32 v180, v182
	v_permlane16_swap_b32_e32 v181, v183
	global_store_dwordx4 v[64:65], v[180:183], off offset:256
	s_and_b64 vcc, exec, s[50:51]
	s_cbranch_vccz .LBB0_1169

.LBB0_1187:
	s_andn2_b64 vcc, exec, s[50:51]
	s_cbranch_vccnz .LBB0_1189
	s_waitcnt vmcnt(0) lgkmcnt(0)
	v_pk_mul_f32 v[32:33], v[70:71], v[62:63]
	v_pk_mul_f32 v[36:37], v[70:71], v[58:59]
	v_pk_fma_f32 v[32:33], v[66:67], v[58:59], v[32:33] neg_lo:[0,0,1] neg_hi:[0,0,1]
	v_pk_mul_f32 v[34:35], v[68:69], v[60:61]
	v_cndmask_b32_e64 v33, v67, v33, s[46:47]
	v_cndmask_b32_e64 v32, v66, v32, s[46:47]
	v_pk_fma_f32 v[36:37], v[66:67], v[62:63], v[36:37]
	v_pk_mul_f32 v[66:67], v[32:33], s[28:29] op_sel_hi:[1,0]
	v_pk_fma_f32 v[34:35], v[64:65], v[56:57], v[34:35] neg_lo:[0,0,1] neg_hi:[0,0,1]
	v_pk_mul_f32 v[38:39], v[68:69], v[56:57]
	v_cndmask_b32_e64 v67, v33, v67, s[48:49]
	v_cndmask_b32_e64 v66, v32, v66, s[48:49]
	v_mov_b64_e32 v[32:33], s[90:91]
	v_pk_fma_f32 v[38:39], v[64:65], v[60:61], v[38:39]
	v_cndmask_b32_e64 v35, v65, v35, s[46:47]
	v_cndmask_b32_e64 v34, v64, v34, s[46:47]
	v_mad_i64_i32 v[32:33], s[24:25], v200, s85, v[32:33]
	v_cndmask_b32_e64 v37, v71, v37, s[46:47]
	v_cndmask_b32_e64 v36, v70, v36, s[46:47]
	v_cndmask_b32_e64 v39, v69, v39, s[46:47]
	v_cndmask_b32_e64 v38, v68, v38, s[46:47]
	v_pk_mul_f32 v[64:65], v[34:35], s[28:29] op_sel_hi:[1,0]
	v_lshl_add_u64 v[32:33], s[26:27], 1, v[32:33]
	s_lshl_b32 s68, s92, 1
	v_pk_mul_f32 v[68:69], v[38:39], s[28:29] op_sel_hi:[1,0]
	v_pk_mul_f32 v[70:71], v[36:37], s[28:29] op_sel_hi:[1,0]
	v_cndmask_b32_e64 v35, v35, v65, s[48:49]
	v_cndmask_b32_e64 v34, v34, v64, s[48:49]
	v_lshl_add_u64 v[32:33], v[32:33], 0, s[68:69]
	v_cndmask_b32_e64 v37, v37, v71, s[48:49]
	v_cndmask_b32_e64 v36, v36, v70, s[48:49]
	v_cndmask_b32_e64 v39, v39, v69, s[48:49]
	v_cndmask_b32_e64 v38, v38, v68, s[48:49]
	v_lshl_add_u64 v[32:33], v[32:33], 0, v[98:99]
	v_cvt_pk_bf16_f32 v180, v34, v35
	v_cvt_pk_bf16_f32 v181, v66, v67
	v_cvt_pk_bf16_f32 v182, v38, v39
	v_cvt_pk_bf16_f32 v183, v36, v37
	s_nop 1
	v_permlane16_swap_b32_e32 v180, v182
	v_permlane16_swap_b32_e32 v181, v183
	global_store_dwordx4 v[32:33], v[180:183], off
	v_pk_mul_f32 v[34:35], v[26:27], v[62:63]
	v_pk_mul_f32 v[36:37], v[24:25], v[60:61]
	v_pk_fma_f32 v[34:35], v[30:31], v[58:59], v[34:35] neg_lo:[0,0,1] neg_hi:[0,0,1]
	v_pk_fma_f32 v[36:37], v[28:29], v[56:57], v[36:37] neg_lo:[0,0,1] neg_hi:[0,0,1]
	v_pk_mul_f32 v[38:39], v[26:27], v[58:59]
	v_pk_mul_f32 v[56:57], v[24:25], v[56:57]
	s_and_b64 vcc, s[56:57], s[18:19]
	v_pk_fma_f32 v[56:57], v[28:29], v[60:61], v[56:57]
	v_pk_fma_f32 v[38:39], v[30:31], v[62:63], v[38:39]
	v_cndmask_b32_e32 v35, v31, v35, vcc
	v_cndmask_b32_e32 v34, v30, v34, vcc
	v_cndmask_b32_e32 v37, v29, v37, vcc
	v_cndmask_b32_e32 v36, v28, v36, vcc
	v_cndmask_b32_e32 v39, v27, v39, vcc
	v_cndmask_b32_e32 v38, v26, v38, vcc
	v_cndmask_b32_e32 v57, v25, v57, vcc
	v_cndmask_b32_e32 v56, v24, v56, vcc
	v_pk_mul_f32 v[36:37], v[36:37], s[28:29] op_sel_hi:[1,0]
	v_pk_mul_f32 v[34:35], v[34:35], s[28:29] op_sel_hi:[1,0]
	v_pk_mul_f32 v[56:57], v[56:57], s[28:29] op_sel_hi:[1,0]
	v_pk_mul_f32 v[38:39], v[38:39], s[28:29] op_sel_hi:[1,0]
	v_cndmask_b32_e64 v31, v31, v35, s[48:49]
	v_cndmask_b32_e64 v30, v30, v34, s[48:49]
	v_cndmask_b32_e64 v29, v29, v37, s[48:49]
	v_cndmask_b32_e64 v28, v28, v36, s[48:49]
	v_cndmask_b32_e64 v27, v27, v39, s[48:49]
	v_cndmask_b32_e64 v26, v26, v38, s[48:49]
	v_cndmask_b32_e64 v34, v25, v57, s[48:49]
	v_cndmask_b32_e64 v35, v24, v56, s[48:49]
	v_cvt_pk_bf16_f32 v180, v28, v29
	v_cvt_pk_bf16_f32 v181, v30, v31
	s_movk_i32 s68, 0x21ff
	v_cvt_pk_bf16_f32 v182, v35, v34
	v_cvt_pk_bf16_f32 v183, v26, v27
	s_nop 1
	v_permlane16_swap_b32_e32 v180, v182
	v_permlane16_swap_b32_e32 v181, v183
	global_store_dwordx4 v[32:33], v[180:183], off offset:256

.LBB0_1205:
	s_waitcnt vmcnt(0) lgkmcnt(0)
	v_pk_mul_f32 v[16:17], v[30:31], v[10:11]
	v_pk_mul_f32 v[20:21], v[30:31], v[14:15]
	v_pk_fma_f32 v[16:17], v[26:27], v[14:15], v[16:17] neg_lo:[0,0,1] neg_hi:[0,0,1]
	v_pk_mul_f32 v[18:19], v[28:29], v[8:9]
	v_cndmask_b32_e64 v17, v27, v17, s[46:47]
	v_cndmask_b32_e64 v16, v26, v16, s[46:47]
	v_pk_fma_f32 v[20:21], v[26:27], v[10:11], v[20:21]
	v_pk_mul_f32 v[26:27], v[16:17], s[28:29] op_sel_hi:[1,0]
	v_pk_fma_f32 v[18:19], v[24:25], v[12:13], v[18:19] neg_lo:[0,0,1] neg_hi:[0,0,1]
	v_pk_mul_f32 v[22:23], v[28:29], v[12:13]
	v_cndmask_b32_e64 v27, v17, v27, s[48:49]
	v_cndmask_b32_e64 v26, v16, v26, s[48:49]
	v_mov_b64_e32 v[16:17], s[90:91]
	v_pk_fma_f32 v[22:23], v[24:25], v[8:9], v[22:23]
	v_cndmask_b32_e64 v19, v25, v19, s[46:47]
	v_cndmask_b32_e64 v18, v24, v18, s[46:47]
	v_mad_i64_i32 v[16:17], s[24:25], v198, s85, v[16:17]
	v_cndmask_b32_e64 v21, v31, v21, s[46:47]
	v_cndmask_b32_e64 v20, v30, v20, s[46:47]
	v_cndmask_b32_e64 v23, v29, v23, s[46:47]
	v_cndmask_b32_e64 v22, v28, v22, s[46:47]
	v_pk_mul_f32 v[24:25], v[18:19], s[28:29] op_sel_hi:[1,0]
	v_lshl_add_u64 v[16:17], s[26:27], 1, v[16:17]
	s_lshl_b32 s68, s92, 1
	v_pk_mul_f32 v[28:29], v[22:23], s[28:29] op_sel_hi:[1,0]
	v_pk_mul_f32 v[30:31], v[20:21], s[28:29] op_sel_hi:[1,0]
	v_cndmask_b32_e64 v19, v19, v25, s[48:49]
	v_cndmask_b32_e64 v18, v18, v24, s[48:49]
	v_lshl_add_u64 v[16:17], v[16:17], 0, s[68:69]
	v_cndmask_b32_e64 v21, v21, v31, s[48:49]
	v_cndmask_b32_e64 v20, v20, v30, s[48:49]
	v_cndmask_b32_e64 v23, v23, v29, s[48:49]
	v_cndmask_b32_e64 v22, v22, v28, s[48:49]
	v_lshl_add_u64 v[16:17], v[16:17], 0, v[98:99]
	v_cvt_pk_bf16_f32 v180, v18, v19
	v_cvt_pk_bf16_f32 v181, v26, v27
	v_cvt_pk_bf16_f32 v182, v22, v23
	v_cvt_pk_bf16_f32 v183, v20, v21
	s_nop 1
	v_permlane16_swap_b32_e32 v180, v182
	v_permlane16_swap_b32_e32 v181, v183
	global_store_dwordx4 v[16:17], v[180:183], off
	v_pk_mul_f32 v[18:19], v[2:3], v[10:11]
	v_pk_mul_f32 v[20:21], v[0:1], v[8:9]
	v_pk_fma_f32 v[18:19], v[6:7], v[14:15], v[18:19] neg_lo:[0,0,1] neg_hi:[0,0,1]
	v_pk_fma_f32 v[20:21], v[4:5], v[12:13], v[20:21] neg_lo:[0,0,1] neg_hi:[0,0,1]
	v_pk_mul_f32 v[14:15], v[2:3], v[14:15]
	v_pk_mul_f32 v[12:13], v[0:1], v[12:13]
	s_and_b64 vcc, s[56:57], s[18:19]
	v_pk_fma_f32 v[8:9], v[4:5], v[8:9], v[12:13]
	v_pk_fma_f32 v[10:11], v[6:7], v[10:11], v[14:15]
	v_cndmask_b32_e32 v13, v7, v19, vcc
	v_cndmask_b32_e32 v12, v6, v18, vcc
	v_cndmask_b32_e32 v15, v5, v21, vcc
	v_cndmask_b32_e32 v14, v4, v20, vcc
	v_cndmask_b32_e32 v11, v3, v11, vcc
	v_cndmask_b32_e32 v10, v2, v10, vcc
	v_cndmask_b32_e32 v9, v1, v9, vcc
	v_cndmask_b32_e32 v8, v0, v8, vcc
	v_pk_mul_f32 v[14:15], v[14:15], s[28:29] op_sel_hi:[1,0]
	v_pk_mul_f32 v[12:13], v[12:13], s[28:29] op_sel_hi:[1,0]
	v_pk_mul_f32 v[8:9], v[8:9], s[28:29] op_sel_hi:[1,0]
	v_pk_mul_f32 v[10:11], v[10:11], s[28:29] op_sel_hi:[1,0]
	v_cndmask_b32_e64 v7, v7, v13, s[48:49]
	v_cndmask_b32_e64 v6, v6, v12, s[48:49]
	v_cndmask_b32_e64 v5, v5, v15, s[48:49]
	v_cndmask_b32_e64 v4, v4, v14, s[48:49]
	v_cndmask_b32_e64 v3, v3, v11, s[48:49]
	v_cndmask_b32_e64 v2, v2, v10, s[48:49]
	v_cndmask_b32_e64 v9, v1, v9, s[48:49]
	v_cndmask_b32_e64 v8, v0, v8, s[48:49]
	v_cvt_pk_bf16_f32 v180, v4, v5
	v_cvt_pk_bf16_f32 v181, v6, v7
	s_movk_i32 s68, 0x21ff
	v_cvt_pk_bf16_f32 v182, v8, v9
	v_cvt_pk_bf16_f32 v183, v2, v3
	s_nop 1
	v_permlane16_swap_b32_e32 v180, v182
	v_permlane16_swap_b32_e32 v181, v183
	global_store_dwordx4 v[16:17], v[180:183], off offset:256
	s_andn2_b64 vcc, exec, s[44:45]
	s_mov_b64 s[18:19], -1
	s_cbranch_vccnz .LBB0_1058
